# small_gemm: skip the dummy trailing stage re-loads in the last NS-1 K iterations of all seven loops (tighter counted vmcnt there), on top of up-phase K-rotation
# speedup vs baseline: 1.0093x; 1.0093x over previous
; #define LAS __attribute__((address_space(3)))
; DI u32x4 pack8(const f32x4 v0, const f32x4 v1) { u32x4 w; w.x = pk2(v0[0], v0[1]); w.y = pk2(v0[2], v0[3]); w.z = pk2(v1[0], v1[1]); w.w = pk2(v1[2], v1[3]); return w; }
; DI float silu_f(float x) { return x * frcp(1.0f + fexp(-x)); }
;     DI void row8(int row, int col, f32x4 v0, f32x4 v1, float, int fq) const { row8p(row, col, v0, v1, pre(row, col), fq); }
;     DI void row8(int row, int col, f32x4 v0, f32x4 v1, float r, int) const {
;         v0 = v0 * r; v1 = v1 * r;
;         if (col >= 2048) {
; #pragma unroll
;             for (int j = 0; j < 4; ++j) { v0[j] = silu_f(v0[j]); v1[j] = silu_f(v1[j]); } }
;         *(u32x4*)(QKVG + (size_t)row * 3072 + col) = pack8(v0, v1);
;     }
; template <int RA, int NP, int NS, int KT, class R8>
; DI void small_gemm(LAS unsigned char* lds, const bf16* __restrict__ A, const bf16* __restrict__ Bt, int K, int row_base, int col_base, const R8& e, int tid, int wave, int lane) {
;     ...
;     for (int st = 0; st < NT; ++st) {
;         asm volatile("s_waitcnt vmcnt(%0)" :: "n"((NS - 2) * L) : "memory");
;         __builtin_amdgcn_s_barrier();
;         asm volatile("" ::: "memory");
;         { const int nslot = (st + NS - 1) % NS; SG_STAGE(st + NS - 1, nslot); }
;         const LAS unsigned char* sb0 = lds + (st % NS) * STAGE;
; #pragma unroll
;         for (int t = 0; t < KT; ++t) {
;             const LAS unsigned char* sb = sb0 + t * SUB;
;             bf16x8 af[RA][2], bfr[NP][2][2];
; #pragma unroll
;             for (int ra = 0; ra < RA; ++ra) { af[ra][0] = *(const LAS bf16x8*)(sb + aoff[ra]); af[ra][1] = *(const LAS bf16x8*)(sb + aoff[ra] + 1024); }
; #pragma unroll
;             for (int np = 0; np < NP; ++np)
; #pragma unroll
;                 for (int n = 0; n < 2; ++n) { bfr[np][n][0] = *(const LAS bf16x8*)(sb + boff[np][n]); bfr[np][n][1] = *(const LAS bf16x8*)(sb + boff[np][n] + 1024); }
; #pragma unroll
;             for (int ks = 0; ks < 2; ++ks)
; #pragma unroll
;                 for (int ra = 0; ra < RA; ++ra)
; #pragma unroll
;                     for (int np = 0; np < NP; ++np) { acc[ra][np][0] = __builtin_amdgcn_mfma_f32_16x16x32_bf16(bfr[np][0][ks], af[ra][ks], acc[ra][np][0], 0, 0, 0); acc[ra][np][1] = __builtin_amdgcn_mfma_f32_16x16x32_bf16(bfr[np][1][ks], af[ra][ks], acc[ra][np][1], 0, 0, 0); }
;         }
;     }
.LBB0_226:
	s_mul_i32 s19, s12, 0xab
	s_bfe_u32 s19, s19, 0x70009
	s_mul_i32 s19, s19, 3
	s_sub_i32 s19, s12, s19
	s_and_b32 s19, s19, 0xff
	s_and_b32 s20, s15, 0x3c0
	s_mul_i32 s19, s19, 0xa000
	s_lshl_b32 s34, s20, 1
	s_add_i32 s19, s16, s19
	s_waitcnt vmcnt(5)
	s_cmp_lt_u32 s14, 0x96000
	s_cbranch_scc1 .Lsgw4
	s_waitcnt vmcnt(0)
.Lsgw4:
	s_barrier
	s_cmp_ge_u32 s14, 0x8c000
	s_cbranch_scc1 .Lsgn4
	v_lshl_add_u64 v[54:55], v[46:47], 0, s[34:35]
	s_mov_b32 m0, s19
	v_lshl_add_u64 v[56:57], v[44:45], 0, s[34:35]
	global_load_lds_dwordx4 v[54:55], off
	s_add_i32 m0, s19, 0x2000
	v_lshl_add_u64 v[58:59], v[56:57], 0, s[58:59]
	global_load_lds_dwordx4 v[56:57], off
	s_add_i32 m0, s19, 0x4000
	v_lshl_add_u64 v[60:61], v[56:57], 0, s[50:51]
	global_load_lds_dwordx4 v[58:59], off
	s_add_i32 m0, s19, 0x6000
	v_lshl_add_u64 v[62:63], v[56:57], 0, s[60:61]
	global_load_lds_dwordx4 v[60:61], off
	s_add_i32 m0, s19, 0x8000
	global_load_lds_dwordx4 v[62:63], off
.Lsgn4:
	s_mul_hi_u32 s18, s17, 0xaaaaaaab
	s_lshr_b32 s18, s18, 1
	s_mul_i32 s18, s18, 0x1e000
	s_add_i32 s22, s13, s14
	v_subrev_u32_e32 v64, s18, v50
	s_add_i32 s21, s14, 0
	v_subrev_u32_e32 v65, s18, v53
	v_subrev_u32_e32 v66, s18, v51
	v_add_u32_e32 v76, s22, v64
	v_add_u32_e32 v74, s21, v66
	v_add_u32_e32 v75, s21, v65
	ds_read_b128 v[54:57], v76 offset:8192
	ds_read_b128 v[58:61], v74
	ds_read_b128 v[62:65], v76 offset:10240
	ds_read_b128 v[66:69], v76 offset:12288
	ds_read_b128 v[70:73], v76 offset:14336
	s_waitcnt lgkmcnt(0)
	v_mfma_f32_16x16x32_bf16 v[28:31], v[54:57], v[58:61], v[28:31]
	s_add_i32 s17, s17, 1
	s_add_i32 s14, s14, 0xa000
	s_add_i32 s15, s15, 64
	v_mfma_f32_16x16x32_bf16 v[32:35], v[62:65], v[58:61], v[32:35]
	s_add_i32 s12, s12, 1
	s_cmp_eq_u32 s14, 0xa0000
	v_mfma_f32_16x16x32_bf16 v[20:23], v[66:69], v[58:61], v[20:23]
	v_mfma_f32_16x16x32_bf16 v[24:27], v[70:73], v[58:61], v[24:27]
	ds_read_b128 v[58:61], v75
	s_waitcnt lgkmcnt(0)
	v_mfma_f32_16x16x32_bf16 v[16:19], v[54:57], v[58:61], v[16:19]
	v_subrev_u32_e32 v54, s18, v52
	v_add_u32_e32 v75, s21, v54
	ds_read_b128 v[54:57], v76 offset:9216
	v_mfma_f32_16x16x32_bf16 v[12:15], v[62:65], v[58:61], v[12:15]
	ds_read_b128 v[62:65], v76 offset:11264
	v_mfma_f32_16x16x32_bf16 v[4:7], v[66:69], v[58:61], v[4:7]
	ds_read_b128 v[66:69], v76 offset:13312
	v_mfma_f32_16x16x32_bf16 v[8:11], v[70:73], v[58:61], v[8:11]
	ds_read_b128 v[70:73], v76 offset:15360
	ds_read_b128 v[58:61], v74 offset:1024
	s_waitcnt lgkmcnt(0)
	v_mfma_f32_16x16x32_bf16 v[28:31], v[54:57], v[58:61], v[28:31]
	v_mfma_f32_16x16x32_bf16 v[32:35], v[62:65], v[58:61], v[32:35]
	v_mfma_f32_16x16x32_bf16 v[20:23], v[66:69], v[58:61], v[20:23]
	v_mfma_f32_16x16x32_bf16 v[24:27], v[70:73], v[58:61], v[24:27]
	ds_read_b128 v[58:61], v75
	s_waitcnt lgkmcnt(0)
	v_mfma_f32_16x16x32_bf16 v[16:19], v[54:57], v[58:61], v[16:19]
	v_mfma_f32_16x16x32_bf16 v[12:15], v[62:65], v[58:61], v[12:15]
	v_mfma_f32_16x16x32_bf16 v[4:7], v[66:69], v[58:61], v[4:7]
	v_mfma_f32_16x16x32_bf16 v[8:11], v[70:73], v[58:61], v[8:11]
	s_cbranch_scc0 .LBB0_226
	v_add_f32_e32 v41, v41, v43
	s_lshl_b32 s4, s4, 2
	v_fmamk_f32 v41, v41, 0x3a800000, v1
	s_sub_i32 s4, s3, s4
	v_rsq_f32_e32 v46, v41
	s_lshl_b32 s4, s4, 6
	s_add_i32 s4, s4, s5
	s_waitcnt vmcnt(0)
	s_barrier
	v_or_b32_e32 v44, s4, v157
	v_pk_mul_f32 v[30:31], v[46:47], v[30:31] op_sel_hi:[0,1]
	v_pk_mul_f32 v[28:29], v[46:47], v[28:29] op_sel_hi:[0,1]
	v_pk_mul_f32 v[34:35], v[46:47], v[34:35] op_sel_hi:[0,1]
	v_pk_mul_f32 v[32:33], v[46:47], v[32:33] op_sel_hi:[0,1]
	v_cmp_lt_i32_e32 vcc, s97, v44
	s_and_saveexec_b64 s[4:5], vcc
	s_cbranch_execz .LBB0_229
	v_mul_f32_e32 v41, 0xbfb8aa3b, v28
	v_exp_f32_e32 v41, v41
	s_nop 0
	v_add_f32_e32 v41, 1.0, v41
	v_rcp_f32_e32 v50, v41
	v_mul_f32_e32 v41, 0xbfb8aa3b, v32
	v_exp_f32_e32 v41, v41
	s_nop 0
	v_add_f32_e32 v41, 1.0, v41
	v_rcp_f32_e32 v52, v41
	v_mul_f32_e32 v41, 0xbfb8aa3b, v29
	v_exp_f32_e32 v41, v41
	s_nop 0
	v_add_f32_e32 v41, 1.0, v41
	v_rcp_f32_e32 v51, v41
	v_mul_f32_e32 v41, 0xbfb8aa3b, v33
	v_exp_f32_e32 v41, v41
	v_pk_mul_f32 v[28:29], v[28:29], v[50:51]
	v_add_f32_e32 v41, 1.0, v41
	v_rcp_f32_e32 v53, v41
	v_mul_f32_e32 v41, 0xbfb8aa3b, v30
	v_exp_f32_e32 v41, v41
	v_pk_mul_f32 v[32:33], v[32:33], v[52:53]
	v_add_f32_e32 v41, 1.0, v41
	v_rcp_f32_e32 v54, v41
	v_mul_f32_e32 v41, 0xbfb8aa3b, v34
	v_exp_f32_e32 v41, v41
	s_nop 0
	v_add_f32_e32 v41, 1.0, v41
	v_rcp_f32_e32 v56, v41
	v_mul_f32_e32 v41, 0xbfb8aa3b, v31
	v_exp_f32_e32 v41, v41
	s_nop 0
	v_add_f32_e32 v41, 1.0, v41
	v_rcp_f32_e32 v55, v41
	v_mul_f32_e32 v41, 0xbfb8aa3b, v35
	v_exp_f32_e32 v41, v41
	v_pk_mul_f32 v[30:31], v[30:31], v[54:55]
	v_add_f32_e32 v41, 1.0, v41
	v_rcp_f32_e32 v57, v41
	s_nop 0
	v_pk_mul_f32 v[34:35], v[34:35], v[56:57]

;     DI void row8(int row, int col, f32x4 v0, f32x4 v1, float r, int) const {
;         v0 = v0 * r; v1 = v1 * r;
;         if (col < 1024) {
; #pragma unroll
;             for (int j = 0; j < 4; ++j) { v0[j] = gelu_tanh(v0[j]); v1[j] = gelu_tanh(v1[j]); }
;             *(u32x4*)(GATE + (size_t)row * 1024 + col) = pack8(v0, v1);
;         } else {
;             const int c = col - 1024; float* tail = nullptr;
;             if (row < 16384) { const int t = row & 2047; if (t >= 2045) tail = convP + ((size_t)(row >> 11) * 3 + (t - 2045)) * 1024 + c; }
;             else { const int rr = row - 16384, t = rr & 7; if (t >= 5) tail = convS + ((size_t)(rr >> 3) * 3 + (t - 5)) * 1024 + c; }
;             if (tail) { *(f32x4*)tail = v0; *(f32x4*)(tail + 4) = v1; }
; template <int RA, int NP, int NS, int KT, class R8>
; DI void small_gemm(LAS unsigned char* lds, const bf16* __restrict__ A, const bf16* __restrict__ Bt, int K, int row_base, int col_base, const R8& e, int tid, int wave, int lane) {
;     ...
;     for (int st = 0; st < NT; ++st) {
;         asm volatile("s_waitcnt vmcnt(%0)" :: "n"((NS - 2) * L) : "memory");
;         __builtin_amdgcn_s_barrier();
;         asm volatile("" ::: "memory");
;         { const int nslot = (st + NS - 1) % NS; SG_STAGE(st + NS - 1, nslot); }
;         const LAS unsigned char* sb0 = lds + (st % NS) * STAGE;
; #pragma unroll
;         for (int t = 0; t < KT; ++t) {
;             const LAS unsigned char* sb = sb0 + t * SUB;
;             bf16x8 af[RA][2], bfr[NP][2][2];
; #pragma unroll
;             for (int ra = 0; ra < RA; ++ra) { af[ra][0] = *(const LAS bf16x8*)(sb + aoff[ra]); af[ra][1] = *(const LAS bf16x8*)(sb + aoff[ra] + 1024); }
; #pragma unroll
;             for (int np = 0; np < NP; ++np)
; #pragma unroll
;                 for (int n = 0; n < 2; ++n) { bfr[np][n][0] = *(const LAS bf16x8*)(sb + boff[np][n]); bfr[np][n][1] = *(const LAS bf16x8*)(sb + boff[np][n] + 1024); }
; #pragma unroll
;             for (int ks = 0; ks < 2; ++ks)
; #pragma unroll
;                 for (int ra = 0; ra < RA; ++ra)
; #pragma unroll
;                     for (int np = 0; np < NP; ++np) { acc[ra][np][0] = __builtin_amdgcn_mfma_f32_16x16x32_bf16(bfr[np][0][ks], af[ra][ks], acc[ra][np][0], 0, 0, 0); acc[ra][np][1] = __builtin_amdgcn_mfma_f32_16x16x32_bf16(bfr[np][1][ks], af[ra][ks], acc[ra][np][1], 0, 0, 0); }
;         }
;     }
.LBB0_736:
	s_mul_i32 s12, s9, 0xcd
	s_bfe_u32 s12, s12, 0x6000a
	s_mul_i32 s12, s12, 5
	s_sub_i32 s12, s9, s12
	s_and_b32 s12, s12, 0xff
	s_and_b32 s13, s10, 0x3c0
	s_mulk_i32 s12, 0x6000
	s_lshl_b32 s34, s13, 1
	s_add_i32 s12, s6, s12
	s_waitcnt vmcnt(9)
	s_cmp_lt_u32 s8, 0x4e000
	s_cbranch_scc1 .Lsgw6
	s_waitcnt vmcnt(6)
	s_cmp_lt_u32 s8, 0x54000
	s_cbranch_scc1 .Lsgw6
	s_waitcnt vmcnt(3)
	s_cmp_lt_u32 s8, 0x5a000
	s_cbranch_scc1 .Lsgw6
	s_waitcnt vmcnt(0)
.Lsgw6:
	s_barrier
	s_cmp_ge_u32 s8, 0x48000
	s_cbranch_scc1 .Lsgn6
	v_lshl_add_u64 v[36:37], v[22:23], 0, s[34:35]
	s_mov_b32 m0, s12
	v_lshl_add_u64 v[40:41], v[20:21], 0, s[34:35]
	global_load_lds_dwordx4 v[36:37], off
	s_add_i32 m0, s12, 0x2000
	v_lshl_add_u64 v[42:43], v[40:41], 0, s[58:59]
	global_load_lds_dwordx4 v[40:41], off
	s_add_i32 m0, s12, 0x4000
	global_load_lds_dwordx4 v[42:43], off
.Lsgn6:
	s_mul_hi_u32 s12, s11, 0xcccccccd
	s_lshr_b32 s12, s12, 2
	s_mul_i32 s12, s12, 0x1e000
	s_add_i32 s22, s7, s8
	v_subrev_u32_e32 v35, s12, v30
	s_add_i32 s13, s8, 0
	v_subrev_u32_e32 v39, s12, v31
	v_add_u32_e32 v35, s22, v35
	v_add_u32_e32 v39, s13, v39
	ds_read_b128 v[40:43], v35 offset:8192
	ds_read_b128 v[44:47], v39
	ds_read_b128 v[48:51], v35 offset:10240
	v_subrev_u32_e32 v37, s12, v34
	v_add_u32_e32 v37, s13, v37
	s_waitcnt lgkmcnt(0)
	v_mfma_f32_16x16x32_bf16 v[12:15], v[40:43], v[44:47], v[12:15]
	v_subrev_u32_e32 v36, s12, v32
	v_add_u32_e32 v36, s13, v36
	s_add_i32 s11, s11, 1
	v_mfma_f32_16x16x32_bf16 v[16:19], v[48:51], v[44:47], v[16:19]
	ds_read_b128 v[44:47], v37
	s_addk_i32 s8, 0x6000
	s_add_i32 s10, s10, 64
	s_waitcnt lgkmcnt(0)
	v_mfma_f32_16x16x32_bf16 v[8:11], v[40:43], v[44:47], v[8:11]
	ds_read_b128 v[40:43], v35 offset:9216
	s_add_i32 s9, s9, 1
	s_cmp_eq_u32 s8, 0x60000
	v_mfma_f32_16x16x32_bf16 v[4:7], v[48:51], v[44:47], v[4:7]
	ds_read_b128 v[48:51], v35 offset:11264
	ds_read_b128 v[44:47], v39 offset:1024
	s_waitcnt lgkmcnt(0)
	v_mfma_f32_16x16x32_bf16 v[12:15], v[40:43], v[44:47], v[12:15]
	v_mfma_f32_16x16x32_bf16 v[16:19], v[48:51], v[44:47], v[16:19]
	ds_read_b128 v[44:47], v36
	s_waitcnt lgkmcnt(0)
	v_mfma_f32_16x16x32_bf16 v[8:11], v[40:43], v[44:47], v[8:11]
	v_mfma_f32_16x16x32_bf16 v[4:7], v[48:51], v[44:47], v[4:7]
	s_cbranch_scc0 .LBB0_736
	v_add_f32_e32 v20, v28, v29
	v_fmamk_f32 v20, v20, 0x3a800000, v1
	v_rsq_f32_e32 v32, v20
	s_lshl_b32 s5, s5, 5
	s_add_i32 s5, s5, s4
	s_waitcnt vmcnt(0)
	s_barrier
	v_or_b32_e32 v28, s5, v143
	s_movk_i32 s4, 0x3ff
	v_and_b32_e32 v3, 7, v3
	v_cmp_lt_i32_e64 s[4:5], s4, v28
	v_add_u32_e32 v30, 0xfffffc00, v28
	v_mov_b32_e32 v31, v2
	v_pk_mul_f32 v[22:23], v[32:33], v[14:15] op_sel_hi:[0,1]
	v_pk_mul_f32 v[20:21], v[32:33], v[12:13] op_sel_hi:[0,1]
	v_pk_mul_f32 v[14:15], v[32:33], v[18:19] op_sel_hi:[0,1]
	v_pk_mul_f32 v[12:13], v[32:33], v[16:17] op_sel_hi:[0,1]
	v_subrev_co_u32_e32 v32, vcc, 5, v3
	s_and_saveexec_b64 s[6:7], s[4:5]
	s_xor_b64 s[8:9], exec, s[6:7]
	s_cbranch_execz .LBB0_741
	s_movk_i32 s6, 0x3fff
	s_cmp_lg_u64 s[16:17], 0
	v_cmp_lt_i32_e64 s[6:7], s6, v26
	s_cselect_b64 s[10:11], -1, 0
	s_xor_b64 s[12:13], vcc, -1
	s_and_b64 s[6:7], s[6:7], s[12:13]
	s_and_b64 s[10:11], s[6:7], s[10:11]
	s_and_saveexec_b64 s[6:7], s[10:11]
	s_cbranch_execz .LBB0_740
	v_add_u32_e32 v3, 0xffffc000, v26
	v_lshrrev_b32_e32 v3, 3, v3
	v_mad_u64_u32 v[16:17], s[10:11], v3, 3, v[32:33]
	v_mov_b32_e32 v17, v2
	v_lshlrev_b64 v[16:17], 12, v[16:17]
	v_lshl_add_u64 v[16:17], s[20:21], 0, v[16:17]
	v_lshl_add_u64 v[16:17], v[30:31], 2, v[16:17]
	global_store_dwordx4 v[16:17], v[20:23], off
	global_store_dwordx4 v[16:17], v[12:15], off offset:16

; #define LAS __attribute__((address_space(3)))
; DI float bf_lo(unsigned u) { return __uint_as_float(u << 16); }
;     DI void row8p(int row, int col, f32x4 v0, f32x4 v1, const u32x4 w, int fq) const {
;         f32x4 x0 = (f32x4){bf_lo(w.x), bf_hi(w.x), bf_lo(w.y), bf_hi(w.y)}, x1 = (f32x4){bf_lo(w.z), bf_hi(w.z), bf_lo(w.w), bf_hi(w.w)};
;         x0 = x0 + v0 * scale; x1 = x1 + v1 * scale;
;         *(u32x4*)(XB + (size_t)row * 1024 + col) = pack8(x0, x1);
;         float s = ((x0[0] * x0[0] + x0[1] * x0[1]) + (x0[2] * x0[2] + x0[3] * x0[3])) + ((x1[0] * x1[0] + x1[1] * x1[1]) + (x1[2] * x1[2] + x1[3] * x1[3]));
;         s = xsum32(xsum16(s));
;         if (fq == 0) SS[(size_t)row * 32 + (col >> 5)] = s;
;     }
; template <int RA, int NP, int NS, int KT, class R8>
; DI void small_gemm(LAS unsigned char* lds, const bf16* __restrict__ A, const bf16* __restrict__ Bt, int K, int row_base, int col_base, const R8& e, int tid, int wave, int lane) {
;     ...
;     for (int st = 0; st < NT; ++st) {
;         asm volatile("s_waitcnt vmcnt(%0)" :: "n"((NS - 2) * L) : "memory");
;         __builtin_amdgcn_s_barrier();
;         asm volatile("" ::: "memory");
;         { const int nslot = (st + NS - 1) % NS; SG_STAGE(st + NS - 1, nslot); }
;         const LAS unsigned char* sb0 = lds + (st % NS) * STAGE;
; #pragma unroll
;         for (int t = 0; t < KT; ++t) {
;             const LAS unsigned char* sb = sb0 + t * SUB;
;             bf16x8 af[RA][2], bfr[NP][2][2];
; #pragma unroll
;             for (int ra = 0; ra < RA; ++ra) { af[ra][0] = *(const LAS bf16x8*)(sb + aoff[ra]); af[ra][1] = *(const LAS bf16x8*)(sb + aoff[ra] + 1024); }
; #pragma unroll
;             for (int np = 0; np < NP; ++np)
; #pragma unroll
;                 for (int n = 0; n < 2; ++n) { bfr[np][n][0] = *(const LAS bf16x8*)(sb + boff[np][n]); bfr[np][n][1] = *(const LAS bf16x8*)(sb + boff[np][n] + 1024); }
; #pragma unroll
;             for (int ks = 0; ks < 2; ++ks)
; #pragma unroll
;                 for (int ra = 0; ra < RA; ++ra)
; #pragma unroll
;                     for (int np = 0; np < NP; ++np) { acc[ra][np][0] = __builtin_amdgcn_mfma_f32_16x16x32_bf16(bfr[np][0][ks], af[ra][ks], acc[ra][np][0], 0, 0, 0); acc[ra][np][1] = __builtin_amdgcn_mfma_f32_16x16x32_bf16(bfr[np][1][ks], af[ra][ks], acc[ra][np][1], 0, 0, 0); }
;         }
;     }
.LBB0_1019:
	s_add_i32 s8, s7, 0x18000
	s_and_b32 s9, s6, 0x380
	s_and_b32 s8, s8, 0x18000
	s_lshl_b32 s34, s9, 1
	s_add_i32 s8, s4, s8
	s_waitcnt vmcnt(8)
	s_cmpk_lt_u32 s6, 0x480
	s_cbranch_scc1 .Lsgw0
	s_waitcnt vmcnt(4)
	s_cmpk_lt_u32 s6, 0x500
	s_cbranch_scc1 .Lsgw0
	s_waitcnt vmcnt(0)
.Lsgw0:
	s_barrier
	s_cmpk_ge_u32 s6, 0x400
	s_cbranch_scc1 .Lsgn0
	v_lshl_add_u64 v[26:27], v[22:23], 0, s[34:35]
	s_mov_b32 m0, s8
	v_lshl_add_u64 v[28:29], v[20:21], 0, s[34:35]
	global_load_lds_dwordx4 v[26:27], off
	s_add_i32 m0, s8, 0x2000
	v_lshl_add_u64 v[30:31], v[26:27], 0, s[52:53]
	global_load_lds_dwordx4 v[28:29], off
	s_add_i32 m0, s8, 0x4000
	v_lshl_add_u64 v[32:33], v[28:29], 0, s[52:53]
	global_load_lds_dwordx4 v[30:31], off
	s_add_i32 m0, s8, 0x6000
	global_load_lds_dwordx4 v[32:33], off
.Lsgn0:
	s_and_b32 s8, s7, 0x18000
	s_add_i32 s8, s8, 0
	s_add_i32 s9, s5, s8
	v_add_u32_e32 v42, s8, v25
	v_add_u32_e32 v43, s9, v3
	ds_read_b128 v[26:29], v42 offset:8192
	ds_read_b128 v[30:33], v43
	ds_read_b128 v[34:37], v42 offset:10240
	s_waitcnt lgkmcnt(0)
	v_mfma_f32_16x16x32_bf16 v[8:11], v[26:29], v[30:33], v[8:11]
	ds_read_b128 v[26:29], v42 offset:9216
	ds_read_b128 v[38:41], v43 offset:1024
	s_addk_i32 s6, 0x80
	s_add_i32 s7, s7, 0x8000
	v_mfma_f32_16x16x32_bf16 v[12:15], v[34:37], v[30:33], v[12:15]
	ds_read_b128 v[30:33], v42 offset:11264
	s_cmpk_eq_i32 s6, 0x580
	s_waitcnt lgkmcnt(0)
	v_mfma_f32_16x16x32_bf16 v[8:11], v[26:29], v[38:41], v[8:11]
	ds_read_b128 v[26:29], v42 offset:24576
	ds_read_b128 v[34:37], v43 offset:16384
	v_mfma_f32_16x16x32_bf16 v[12:15], v[30:33], v[38:41], v[12:15]
	ds_read_b128 v[30:33], v42 offset:26624
	s_waitcnt lgkmcnt(0)
	v_mfma_f32_16x16x32_bf16 v[8:11], v[26:29], v[34:37], v[8:11]
	ds_read_b128 v[26:29], v42 offset:25600
	v_mfma_f32_16x16x32_bf16 v[12:15], v[30:33], v[34:37], v[12:15]
	ds_read_b128 v[30:33], v43 offset:17408
	s_waitcnt lgkmcnt(0)
	v_mfma_f32_16x16x32_bf16 v[8:11], v[26:29], v[30:33], v[8:11]
	ds_read_b128 v[26:29], v42 offset:27648
	s_waitcnt lgkmcnt(0)
	v_mfma_f32_16x16x32_bf16 v[12:15], v[26:29], v[30:33], v[12:15]
	s_cbranch_scc0 .LBB0_1019
	s_waitcnt vmcnt(0)
	v_lshlrev_b32_e32 v20, 16, v4
	v_and_b32_e32 v21, 0xffff0000, v4
	v_lshlrev_b32_e32 v4, 16, v5
	v_and_b32_e32 v5, 0xffff0000, v5
	v_lshlrev_b32_e32 v22, 16, v6
	v_and_b32_e32 v23, 0xffff0000, v6
	v_lshlrev_b32_e32 v6, 16, v7
	v_and_b32_e32 v7, 0xffff0000, v7
	v_pk_add_f32 v[10:11], v[10:11], v[4:5]
	v_pk_add_f32 v[8:9], v[8:9], v[20:21]
	v_pk_add_f32 v[14:15], v[14:15], v[6:7]
	v_pk_add_f32 v[12:13], v[12:13], v[22:23]
	v_cvt_pk_bf16_f32 v4, v8, v9
	v_cvt_pk_bf16_f32 v5, v10, v11
	v_cvt_pk_bf16_f32 v6, v12, v13
	v_cvt_pk_bf16_f32 v7, v14, v15
	s_waitcnt vmcnt(0)
	s_barrier
	global_store_dwordx4 v[18:19], v[4:7], off
	v_mul_f32_e32 v3, v9, v9
	v_fmac_f32_e32 v3, v8, v8
	v_mul_f32_e32 v4, v11, v11
	v_fmac_f32_e32 v4, v10, v10
	v_add_f32_e32 v3, v3, v4
	v_mul_f32_e32 v4, v13, v13
	v_mul_f32_e32 v5, v15, v15
	v_fmac_f32_e32 v4, v12, v12
	v_fmac_f32_e32 v5, v14, v14
	v_add_f32_e32 v4, v4, v5
	v_add_f32_e32 v3, v3, v4
	v_mov_b32_e32 v4, v3
	s_nop 1
	v_permlane16_swap_b32_e32 v3, v4
	v_add_f32_e32 v3, v3, v4
	v_mov_b32_e32 v4, v3
	v_cmp_gt_u32_e32 vcc, 16, v24
	s_nop 0
	v_permlane32_swap_b32_e32 v3, v4
	s_and_saveexec_b64 s[4:5], vcc
	s_cbranch_execz .LBB0_1022
	v_lshlrev_b64 v[6:7], 7, v[16:17]
	s_ashr_i32 s6, s3, 5
	s_ashr_i32 s7, s6, 31
	v_add_f32_e32 v3, v3, v4
	v_lshl_add_u64 v[4:5], s[0:1], 0, v[6:7]
	v_lshl_add_u64 v[4:5], s[6:7], 2, v[4:5]
	global_store_dword v[4:5], v3, off

; #define LAS __attribute__((address_space(3)))
; DI float xsum16(float v) { const unsigned u = __float_as_uint(v); const u32x2p r = __builtin_amdgcn_permlane16_swap(u, u, false, false); return __uint_as_float(r[0]) + __uint_as_float(r[1]); }
; DI float rs_of_row(const float* SS, int row, int fq) {
;     const f32x4 a = *(const f32x4*)(SS + (size_t)row * 32 + 8 * fq), b = *(const f32x4*)(SS + (size_t)row * 32 + 8 * fq + 4);
;     float s = ((a[0] + a[1]) + (a[2] + a[3])) + ((b[0] + b[1]) + (b[2] + b[3]));
;     s = xsum32(xsum16(s));
;     return __builtin_amdgcn_rsqf(s * (1.0f / 1024.0f) + RMS_EPS);
; }
; template <int RA, int NP, int NS, int KT, class R8>
; DI void small_gemm(LAS unsigned char* lds, const bf16* __restrict__ A, const bf16* __restrict__ Bt, int K, int row_base, int col_base, const R8& e, int tid, int wave, int lane) {
;     ...
;     for (int st = 0; st < NT; ++st) {
;         asm volatile("s_waitcnt vmcnt(%0)" :: "n"((NS - 2) * L) : "memory");
;         __builtin_amdgcn_s_barrier();
;         asm volatile("" ::: "memory");
;         { const int nslot = (st + NS - 1) % NS; SG_STAGE(st + NS - 1, nslot); }
;         const LAS unsigned char* sb0 = lds + (st % NS) * STAGE;
; #pragma unroll
;         for (int t = 0; t < KT; ++t) {
;             const LAS unsigned char* sb = sb0 + t * SUB;
;             bf16x8 af[RA][2], bfr[NP][2][2];
; #pragma unroll
;             for (int ra = 0; ra < RA; ++ra) { af[ra][0] = *(const LAS bf16x8*)(sb + aoff[ra]); af[ra][1] = *(const LAS bf16x8*)(sb + aoff[ra] + 1024); }
; #pragma unroll
;             for (int np = 0; np < NP; ++np)
; #pragma unroll
;                 for (int n = 0; n < 2; ++n) { bfr[np][n][0] = *(const LAS bf16x8*)(sb + boff[np][n]); bfr[np][n][1] = *(const LAS bf16x8*)(sb + boff[np][n] + 1024); }
; #pragma unroll
;             for (int ks = 0; ks < 2; ++ks)
; #pragma unroll
;                 for (int ra = 0; ra < RA; ++ra)
; #pragma unroll
;                     for (int np = 0; np < NP; ++np) { acc[ra][np][0] = __builtin_amdgcn_mfma_f32_16x16x32_bf16(bfr[np][0][ks], af[ra][ks], acc[ra][np][0], 0, 0, 0); acc[ra][np][1] = __builtin_amdgcn_mfma_f32_16x16x32_bf16(bfr[np][1][ks], af[ra][ks], acc[ra][np][1], 0, 0, 0); }
;         }
;     }
.LBB0_1116:
	s_add_i32 s19, s18, 0x18000
	s_and_b32 s20, s13, 0x380
	s_and_b32 s19, s19, 0x18000
	s_lshl_b32 s34, s20, 1
	s_add_i32 s19, s4, s19
	s_waitcnt vmcnt(8)
	s_cmpk_lt_u32 s13, 0x480
	s_cbranch_scc1 .Lsgw1
	s_waitcnt vmcnt(4)
	s_cmpk_lt_u32 s13, 0x500
	s_cbranch_scc1 .Lsgw1
	s_waitcnt vmcnt(0)
.Lsgw1:
	s_barrier
	s_cmpk_ge_u32 s13, 0x400
	s_cbranch_scc1 .Lsgn1
	v_lshl_add_u64 v[28:29], v[24:25], 0, s[34:35]
	s_mov_b32 m0, s19
	v_lshl_add_u64 v[30:31], v[22:23], 0, s[34:35]
	global_load_lds_dwordx4 v[28:29], off
	s_add_i32 m0, s19, 0x2000
	v_lshl_add_u64 v[32:33], v[28:29], 0, s[52:53]
	global_load_lds_dwordx4 v[30:31], off
	s_add_i32 m0, s19, 0x4000
	v_lshl_add_u64 v[34:35], v[30:31], 0, s[52:53]
	global_load_lds_dwordx4 v[32:33], off
	s_add_i32 m0, s19, 0x6000
	global_load_lds_dwordx4 v[34:35], off
.Lsgn1:
	s_and_b32 s19, s18, 0x18000
	s_add_i32 s19, s19, 0
	s_add_i32 s20, s12, s19
	v_add_u32_e32 v44, s19, v27
	v_add_u32_e32 v45, s20, v26
	ds_read_b128 v[28:31], v44 offset:8192
	ds_read_b128 v[32:35], v45
	ds_read_b128 v[36:39], v44 offset:10240
	s_waitcnt lgkmcnt(0)
	v_mfma_f32_16x16x32_bf16 v[12:15], v[28:31], v[32:35], v[12:15]
	ds_read_b128 v[28:31], v44 offset:9216
	ds_read_b128 v[40:43], v45 offset:1024
	s_addk_i32 s13, 0x80
	s_add_i32 s18, s18, 0x8000
	v_mfma_f32_16x16x32_bf16 v[16:19], v[36:39], v[32:35], v[16:19]
	ds_read_b128 v[32:35], v44 offset:11264
	s_cmpk_lg_i32 s13, 0x580
	s_waitcnt lgkmcnt(0)
	v_mfma_f32_16x16x32_bf16 v[12:15], v[28:31], v[40:43], v[12:15]
	ds_read_b128 v[28:31], v44 offset:24576
	ds_read_b128 v[36:39], v45 offset:16384
	v_mfma_f32_16x16x32_bf16 v[16:19], v[32:35], v[40:43], v[16:19]
	ds_read_b128 v[32:35], v44 offset:26624
	s_waitcnt lgkmcnt(0)
	v_mfma_f32_16x16x32_bf16 v[12:15], v[28:31], v[36:39], v[12:15]
	ds_read_b128 v[28:31], v44 offset:25600
	v_mfma_f32_16x16x32_bf16 v[16:19], v[32:35], v[36:39], v[16:19]
	ds_read_b128 v[32:35], v45 offset:17408
	s_waitcnt lgkmcnt(0)
	v_mfma_f32_16x16x32_bf16 v[12:15], v[28:31], v[32:35], v[12:15]
	ds_read_b128 v[28:31], v44 offset:27648
	s_waitcnt lgkmcnt(0)
	v_mfma_f32_16x16x32_bf16 v[16:19], v[28:31], v[32:35], v[16:19]
	s_cbranch_scc1 .LBB0_1116
	s_waitcnt vmcnt(0)
	v_add_f32_e32 v8, v8, v9
	v_add_f32_e32 v9, v10, v11
	v_add_f32_e32 v4, v4, v5
	v_add_f32_e32 v5, v6, v7
	v_add_f32_e32 v8, v8, v9
	v_add_f32_e32 v4, v4, v5
	v_add_f32_e32 v4, v8, v4
	v_mov_b32_e32 v5, v4
	s_nop 1
	v_permlane16_swap_b32_e32 v4, v5
	v_add_f32_e32 v4, v4, v5
	v_mov_b32_e32 v5, v4
	s_nop 1
	v_permlane32_swap_b32_e32 v4, v5
	v_add_f32_e32 v4, v4, v5
	v_fmamk_f32 v4, v4, 0x3a800000, v1
	v_rsq_f32_e32 v4, v4
	s_lshl_b32 s4, s5, 5
	s_add_i32 s4, s4, s17
	s_waitcnt vmcnt(0)
	v_pk_mul_f32 v[10:11], v[12:13], v[4:5] op_sel_hi:[1,0]
	s_barrier
	v_or_b32_e32 v8, s4, v151
	v_pk_mul_f32 v[6:7], v[14:15], v[4:5] op_sel_hi:[1,0]
	v_pk_mul_f32 v[12:13], v[18:19], v[4:5] op_sel_hi:[1,0]
	v_pk_mul_f32 v[14:15], v[16:17], v[4:5] op_sel_hi:[1,0]
	v_cvt_pk_bf16_f32 v4, v10, v11
	v_lshlrev_b64 v[10:11], 11, v[20:21]
	s_bitcmp1_b32 s27, 0
	v_ashrrev_i32_e32 v9, 31, v8
	v_lshl_add_u64 v[10:11], s[10:11], 0, v[10:11]
	s_cselect_b64 s[4:5], -1, 0
	v_cvt_pk_bf16_f32 v5, v6, v7
	v_cvt_pk_bf16_f32 v6, v14, v15
	v_cvt_pk_bf16_f32 v7, v12, v13
	v_lshl_add_u64 v[8:9], v[8:9], 1, v[10:11]
	s_and_b64 vcc, exec, s[4:5]
	global_store_dwordx4 v[8:9], v[4:7], off
	s_cbranch_vccnz .LBB0_1119
; #define LAS __attribute__((address_space(3)))
; DI void attn_stage_kv(LAS unsigned char* lds, const bf16* KVP, int b, int h, int tid) {
;     const bf16* kbase = KVP + (size_t)(b * 256) * DM + h * 256;
;     u32x4 v[16];
; #pragma unroll
;     for (int i = 0; i < 16; ++i) { const int id = tid + 512 * i, m = id >> 5, ch = id & 31; v[i] = *(const u32x4*)(kbase + (size_t)m * DM + ch * 8); }
; #pragma unroll
;     for (int i = 0; i < 16; ++i) { const int id = tid + 512 * i, m = id >> 5, ch = id & 31; *(LAS u32x4*)(lds + m * KV_PITCH + ch * 16) = v[i]; }
; }
	s_lshl_b64 s[4:5], s[6:7], 22
	s_add_u32 s0, s0, s4
	s_addc_u32 s1, s1, s5
	s_lshl_b32 s3, s3, 19
	s_add_u32 s3, s0, s3
	s_addc_u32 s4, s1, 0
	s_and_b32 s0, s16, 0xffffff00
	s_ashr_i32 s1, s0, 31
	s_lshl_b64 s[0:1], s[0:1], 1
	s_add_u32 s0, s3, s0
	v_add_u32_e32 v6, 0x200, v3
	s_addc_u32 s1, s4, s1
	v_and_b32_e32 v68, 0x1f0, v150
	v_mov_b32_e32 v69, v2
	v_ashrrev_i32_e32 v70, 5, v3
	v_ashrrev_i32_e32 v72, 5, v6
	v_lshl_add_u64 v[4:5], s[0:1], 0, v[68:69]
	s_mov_b64 s[0:1], 0xeb00000
	v_ashrrev_i32_e32 v71, 31, v70
	v_ashrrev_i32_e32 v73, 31, v72
	v_add_u32_e32 v12, 0x400, v3
	v_add_u32_e32 v14, 0x600, v3
	v_lshl_add_u64 v[64:65], v[4:5], 0, s[0:1]
	v_lshlrev_b64 v[4:5], 11, v[70:71]
	v_lshlrev_b64 v[6:7], 11, v[72:73]
	v_ashrrev_i32_e32 v74, 5, v12
	v_ashrrev_i32_e32 v76, 5, v14
	v_lshl_add_u64 v[4:5], v[64:65], 0, v[4:5]
	v_lshl_add_u64 v[8:9], v[64:65], 0, v[6:7]
	v_ashrrev_i32_e32 v75, 31, v74
	v_ashrrev_i32_e32 v77, 31, v76
	v_add_u32_e32 v20, 0x800, v3
	v_add_u32_e32 v22, 0xa00, v3
	global_load_dwordx4 v[4:7], v[4:5], off
	s_nop 0
	global_load_dwordx4 v[8:11], v[8:9], off
	v_lshlrev_b64 v[12:13], 11, v[74:75]
	v_lshlrev_b64 v[14:15], 11, v[76:77]
	v_ashrrev_i32_e32 v78, 5, v20
	v_ashrrev_i32_e32 v80, 5, v22
	v_lshl_add_u64 v[12:13], v[64:65], 0, v[12:13]
	v_lshl_add_u64 v[16:17], v[64:65], 0, v[14:15]
	v_ashrrev_i32_e32 v79, 31, v78
	v_ashrrev_i32_e32 v81, 31, v80
	v_add_u32_e32 v28, 0xc00, v3
	v_add_u32_e32 v30, 0xe00, v3
	global_load_dwordx4 v[12:15], v[12:13], off
	s_nop 0
	global_load_dwordx4 v[16:19], v[16:17], off
	v_lshlrev_b64 v[20:21], 11, v[78:79]
	v_lshlrev_b64 v[22:23], 11, v[80:81]
	v_ashrrev_i32_e32 v82, 5, v28
	v_ashrrev_i32_e32 v84, 5, v30
	v_lshl_add_u64 v[20:21], v[64:65], 0, v[20:21]
	v_lshl_add_u64 v[24:25], v[64:65], 0, v[22:23]
	v_ashrrev_i32_e32 v83, 31, v82
	v_ashrrev_i32_e32 v85, 31, v84
	v_add_u32_e32 v36, 0x1000, v3
	v_add_u32_e32 v38, 0x1200, v3
	global_load_dwordx4 v[20:23], v[20:21], off
	s_nop 0
	global_load_dwordx4 v[24:27], v[24:25], off
	v_lshlrev_b64 v[28:29], 11, v[82:83]
	v_lshlrev_b64 v[30:31], 11, v[84:85]
	v_ashrrev_i32_e32 v86, 5, v36
	v_ashrrev_i32_e32 v88, 5, v38
	v_lshl_add_u64 v[28:29], v[64:65], 0, v[28:29]
	v_lshl_add_u64 v[32:33], v[64:65], 0, v[30:31]
	v_ashrrev_i32_e32 v87, 31, v86
	v_ashrrev_i32_e32 v89, 31, v88
	v_add_u32_e32 v44, 0x1400, v3
	v_add_u32_e32 v46, 0x1600, v3
	global_load_dwordx4 v[28:31], v[28:29], off
	s_nop 0
	global_load_dwordx4 v[32:35], v[32:33], off
	v_lshlrev_b64 v[36:37], 11, v[86:87]
	v_lshlrev_b64 v[38:39], 11, v[88:89]
	v_ashrrev_i32_e32 v90, 5, v44
	v_ashrrev_i32_e32 v92, 5, v46
	v_lshl_add_u64 v[36:37], v[64:65], 0, v[36:37]
	v_lshl_add_u64 v[40:41], v[64:65], 0, v[38:39]
	v_ashrrev_i32_e32 v91, 31, v90
	v_ashrrev_i32_e32 v93, 31, v92
	v_add_u32_e32 v52, 0x1800, v3
	v_add_u32_e32 v54, 0x1a00, v3
	global_load_dwordx4 v[36:39], v[36:37], off
	s_nop 0
	global_load_dwordx4 v[40:43], v[40:41], off
	v_lshlrev_b64 v[44:45], 11, v[90:91]
	v_lshlrev_b64 v[46:47], 11, v[92:93]
	v_ashrrev_i32_e32 v94, 5, v52
	v_ashrrev_i32_e32 v96, 5, v54
	v_add_u32_e32 v60, 0x1c00, v3
	v_lshl_add_u64 v[44:45], v[64:65], 0, v[44:45]
	v_lshl_add_u64 v[48:49], v[64:65], 0, v[46:47]
	v_ashrrev_i32_e32 v95, 31, v94
	v_ashrrev_i32_e32 v97, 31, v96
	v_ashrrev_i32_e32 v98, 5, v60
	v_add_u32_e32 v3, 0x1e00, v3
	global_load_dwordx4 v[44:47], v[44:45], off
	s_nop 0
	global_load_dwordx4 v[48:51], v[48:49], off
	v_lshlrev_b64 v[52:53], 11, v[94:95]
	v_lshlrev_b64 v[54:55], 11, v[96:97]
	v_ashrrev_i32_e32 v99, 31, v98
	v_ashrrev_i32_e32 v100, 5, v3
	v_lshl_add_u64 v[52:53], v[64:65], 0, v[52:53]
	v_lshl_add_u64 v[56:57], v[64:65], 0, v[54:55]
	v_lshlrev_b64 v[60:61], 11, v[98:99]
	v_ashrrev_i32_e32 v101, 31, v100
	global_load_dwordx4 v[52:55], v[52:53], off
	s_nop 0
	global_load_dwordx4 v[56:59], v[56:57], off
	v_lshl_add_u64 v[60:61], v[64:65], 0, v[60:61]
	v_lshlrev_b64 v[66:67], 11, v[100:101]
	global_load_dwordx4 v[60:63], v[60:61], off
	v_lshl_add_u64 v[64:65], v[64:65], 0, v[66:67]
	global_load_dwordx4 v[64:67], v[64:65], off
	v_add_u32_e32 v68, 0, v68
	v_mad_u64_u32 v[70:71], s[0:1], v70, s69, v[68:69]
	s_waitcnt vmcnt(15)
	ds_write_b128 v70, v[4:7]
	v_mad_u64_u32 v[4:5], s[0:1], v72, s69, v[68:69]
	s_waitcnt vmcnt(14)
	ds_write_b128 v4, v[8:11]
	v_mad_u64_u32 v[4:5], s[0:1], v74, s69, v[68:69]
	s_waitcnt vmcnt(13)
	ds_write_b128 v4, v[12:15]
	v_mad_u64_u32 v[4:5], s[0:1], v76, s69, v[68:69]
	s_waitcnt vmcnt(12)
	ds_write_b128 v4, v[16:19]
	v_mad_u64_u32 v[4:5], s[0:1], v78, s69, v[68:69]
	s_waitcnt vmcnt(11)
	ds_write_b128 v4, v[20:23]
	v_mad_u64_u32 v[4:5], s[0:1], v80, s69, v[68:69]
	s_waitcnt vmcnt(10)
	ds_write_b128 v4, v[24:27]
	v_mad_u64_u32 v[4:5], s[0:1], v82, s69, v[68:69]
	s_waitcnt vmcnt(9)
	ds_write_b128 v4, v[28:31]
	v_mad_u64_u32 v[4:5], s[0:1], v84, s69, v[68:69]
	s_waitcnt vmcnt(8)
	ds_write_b128 v4, v[32:35]
	v_mad_u64_u32 v[4:5], s[0:1], v86, s69, v[68:69]
	s_waitcnt vmcnt(7)
	ds_write_b128 v4, v[36:39]
	v_mad_u64_u32 v[4:5], s[0:1], v88, s69, v[68:69]
	s_waitcnt vmcnt(6)
	ds_write_b128 v4, v[40:43]
	v_mad_u64_u32 v[4:5], s[0:1], v90, s69, v[68:69]
	s_waitcnt vmcnt(5)
	ds_write_b128 v4, v[44:47]
	v_mad_u64_u32 v[4:5], s[0:1], v92, s69, v[68:69]
	s_waitcnt vmcnt(4)
	ds_write_b128 v4, v[48:51]
	v_mad_u64_u32 v[4:5], s[0:1], v94, s69, v[68:69]
	s_waitcnt vmcnt(3)
	ds_write_b128 v4, v[52:55]
	v_mad_u64_u32 v[4:5], s[0:1], v96, s69, v[68:69]
	s_waitcnt vmcnt(2)
	ds_write_b128 v4, v[56:59]
	v_mad_u64_u32 v[4:5], s[0:1], v98, s69, v[68:69]
	s_waitcnt vmcnt(1)
	ds_write_b128 v4, v[60:63]
	v_mad_u64_u32 v[4:5], s[0:1], v100, s69, v[68:69]
	s_waitcnt vmcnt(0)
	ds_write_b128 v4, v[64:67]

; #define LAS __attribute__((address_space(3)))
; DI float bf_lo(unsigned u) { return __uint_as_float(u << 16); }
;     DI void row8p(int row, int col, f32x4 v0, f32x4 v1, const u32x4 w, int fq) const {
;         f32x4 x0 = (f32x4){bf_lo(w.x), bf_hi(w.x), bf_lo(w.y), bf_hi(w.y)}, x1 = (f32x4){bf_lo(w.z), bf_hi(w.z), bf_lo(w.w), bf_hi(w.w)};
;         x0 = x0 + v0 * scale; x1 = x1 + v1 * scale;
;         *(u32x4*)(XB + (size_t)row * 1024 + col) = pack8(x0, x1);
;         float s = ((x0[0] * x0[0] + x0[1] * x0[1]) + (x0[2] * x0[2] + x0[3] * x0[3])) + ((x1[0] * x1[0] + x1[1] * x1[1]) + (x1[2] * x1[2] + x1[3] * x1[3]));
;         s = xsum32(xsum16(s));
;         if (fq == 0) SS[(size_t)row * 32 + (col >> 5)] = s;
;     }
; template <int RA, int NP, int NS, int KT, class R8>
; DI void small_gemm(LAS unsigned char* lds, const bf16* __restrict__ A, const bf16* __restrict__ Bt, int K, int row_base, int col_base, const R8& e, int tid, int wave, int lane) {
;     ...
;     for (int st = 0; st < NT; ++st) {
;         asm volatile("s_waitcnt vmcnt(%0)" :: "n"((NS - 2) * L) : "memory");
;         __builtin_amdgcn_s_barrier();
;         asm volatile("" ::: "memory");
;         { const int nslot = (st + NS - 1) % NS; SG_STAGE(st + NS - 1, nslot); }
;         const LAS unsigned char* sb0 = lds + (st % NS) * STAGE;
; #pragma unroll
;         for (int t = 0; t < KT; ++t) {
;             const LAS unsigned char* sb = sb0 + t * SUB;
;             bf16x8 af[RA][2], bfr[NP][2][2];
; #pragma unroll
;             for (int ra = 0; ra < RA; ++ra) { af[ra][0] = *(const LAS bf16x8*)(sb + aoff[ra]); af[ra][1] = *(const LAS bf16x8*)(sb + aoff[ra] + 1024); }
; #pragma unroll
;             for (int np = 0; np < NP; ++np)
; #pragma unroll
;                 for (int n = 0; n < 2; ++n) { bfr[np][n][0] = *(const LAS bf16x8*)(sb + boff[np][n]); bfr[np][n][1] = *(const LAS bf16x8*)(sb + boff[np][n] + 1024); }
; #pragma unroll
;             for (int ks = 0; ks < 2; ++ks)
; #pragma unroll
;                 for (int ra = 0; ra < RA; ++ra)
; #pragma unroll
;                     for (int np = 0; np < NP; ++np) { acc[ra][np][0] = __builtin_amdgcn_mfma_f32_16x16x32_bf16(bfr[np][0][ks], af[ra][ks], acc[ra][np][0], 0, 0, 0); acc[ra][np][1] = __builtin_amdgcn_mfma_f32_16x16x32_bf16(bfr[np][1][ks], af[ra][ks], acc[ra][np][1], 0, 0, 0); }
;         }
;     }
.LBB0_1306:
	s_add_i32 s10, s9, 0x18000
	s_and_b32 s11, s8, 0x380
	s_and_b32 s10, s10, 0x18000
	s_lshl_b32 s34, s11, 1
	s_add_i32 s10, s4, s10
	s_waitcnt vmcnt(8)
	s_cmpk_lt_u32 s8, 0x480
	s_cbranch_scc1 .Lsgw2
	s_waitcnt vmcnt(4)
	s_cmpk_lt_u32 s8, 0x500
	s_cbranch_scc1 .Lsgw2
	s_waitcnt vmcnt(0)
.Lsgw2:
	s_barrier
	s_cmpk_ge_u32 s8, 0x400
	s_cbranch_scc1 .Lsgn2
	v_lshl_add_u64 v[26:27], v[22:23], 0, s[34:35]
	s_mov_b32 m0, s10
	v_lshl_add_u64 v[28:29], v[20:21], 0, s[34:35]
	global_load_lds_dwordx4 v[26:27], off
	s_add_i32 m0, s10, 0x2000
	v_lshl_add_u64 v[30:31], v[26:27], 0, s[52:53]
	global_load_lds_dwordx4 v[28:29], off
	s_add_i32 m0, s10, 0x4000
	v_lshl_add_u64 v[32:33], v[28:29], 0, s[52:53]
	global_load_lds_dwordx4 v[30:31], off
	s_add_i32 m0, s10, 0x6000
	global_load_lds_dwordx4 v[32:33], off
.Lsgn2:
	s_and_b32 s10, s9, 0x18000
	s_add_i32 s10, s10, 0
	s_add_i32 s11, s5, s10
	v_add_u32_e32 v42, s10, v25
	v_add_u32_e32 v43, s11, v3
	ds_read_b128 v[26:29], v42 offset:8192
	ds_read_b128 v[30:33], v43
	ds_read_b128 v[34:37], v42 offset:10240
	s_waitcnt lgkmcnt(0)
	v_mfma_f32_16x16x32_bf16 v[8:11], v[26:29], v[30:33], v[8:11]
	ds_read_b128 v[26:29], v42 offset:9216
	ds_read_b128 v[38:41], v43 offset:1024
	s_addk_i32 s8, 0x80
	s_add_i32 s9, s9, 0x8000
	v_mfma_f32_16x16x32_bf16 v[12:15], v[34:37], v[30:33], v[12:15]
	ds_read_b128 v[30:33], v42 offset:11264
	s_cmpk_eq_i32 s8, 0x580
	s_waitcnt lgkmcnt(0)
	v_mfma_f32_16x16x32_bf16 v[8:11], v[26:29], v[38:41], v[8:11]
	ds_read_b128 v[26:29], v42 offset:24576
	ds_read_b128 v[34:37], v43 offset:16384
	v_mfma_f32_16x16x32_bf16 v[12:15], v[30:33], v[38:41], v[12:15]
	ds_read_b128 v[30:33], v42 offset:26624
	s_waitcnt lgkmcnt(0)
	v_mfma_f32_16x16x32_bf16 v[8:11], v[26:29], v[34:37], v[8:11]
	ds_read_b128 v[26:29], v42 offset:25600
	v_mfma_f32_16x16x32_bf16 v[12:15], v[30:33], v[34:37], v[12:15]
	ds_read_b128 v[30:33], v43 offset:17408
	s_waitcnt lgkmcnt(0)
	v_mfma_f32_16x16x32_bf16 v[8:11], v[26:29], v[30:33], v[8:11]
	ds_read_b128 v[26:29], v42 offset:27648
	s_waitcnt lgkmcnt(0)
	v_mfma_f32_16x16x32_bf16 v[12:15], v[26:29], v[30:33], v[12:15]
	s_cbranch_scc0 .LBB0_1306
	s_waitcnt vmcnt(0)
	v_lshlrev_b32_e32 v20, 16, v4
	v_and_b32_e32 v21, 0xffff0000, v4
	v_lshlrev_b32_e32 v4, 16, v5
	v_and_b32_e32 v5, 0xffff0000, v5
	v_lshlrev_b32_e32 v22, 16, v6
	v_and_b32_e32 v23, 0xffff0000, v6
	v_lshlrev_b32_e32 v6, 16, v7
	v_and_b32_e32 v7, 0xffff0000, v7
	v_pk_add_f32 v[10:11], v[10:11], v[4:5]
	v_pk_add_f32 v[8:9], v[8:9], v[20:21]
	v_pk_add_f32 v[14:15], v[14:15], v[6:7]
	v_pk_add_f32 v[12:13], v[12:13], v[22:23]
	v_cvt_pk_bf16_f32 v4, v8, v9
	v_cvt_pk_bf16_f32 v5, v10, v11
	v_cvt_pk_bf16_f32 v6, v12, v13
	v_cvt_pk_bf16_f32 v7, v14, v15
	s_waitcnt vmcnt(0)
	s_barrier
	global_store_dwordx4 v[18:19], v[4:7], off
	v_mul_f32_e32 v3, v9, v9
	v_fmac_f32_e32 v3, v8, v8
	v_mul_f32_e32 v4, v11, v11
	v_fmac_f32_e32 v4, v10, v10
	v_add_f32_e32 v3, v3, v4
	v_mul_f32_e32 v4, v13, v13
	v_mul_f32_e32 v5, v15, v15
	v_fmac_f32_e32 v4, v12, v12
	v_fmac_f32_e32 v5, v14, v14
	v_add_f32_e32 v4, v4, v5
	v_add_f32_e32 v3, v3, v4
	v_mov_b32_e32 v4, v3
	s_nop 1
	v_permlane16_swap_b32_e32 v3, v4
	v_add_f32_e32 v3, v3, v4
	v_mov_b32_e32 v4, v3
	v_cmp_gt_u32_e32 vcc, 16, v24
	s_nop 0
	v_permlane32_swap_b32_e32 v3, v4
	s_and_saveexec_b64 s[4:5], vcc
	s_cbranch_execz .LBB0_1309
	v_lshlrev_b64 v[6:7], 7, v[16:17]
	s_ashr_i32 s8, s3, 5
	s_ashr_i32 s9, s8, 31
	v_add_f32_e32 v3, v3, v4
	v_lshl_add_u64 v[4:5], s[0:1], 0, v[6:7]
	v_lshl_add_u64 v[4:5], s[8:9], 2, v[4:5]
	global_store_dword v[4:5], v3, off

; template <int RA, int NP, int NS, int KT, class R8>
; DI void small_gemm(LAS unsigned char* lds, const bf16* __restrict__ A, const bf16* __restrict__ Bt, int K, int row_base, int col_base, const R8& e, int tid, int wave, int lane) {
;     ...
;     for (int st = 0; st < NT; ++st) {
;         asm volatile("s_waitcnt vmcnt(%0)" :: "n"((NS - 2) * L) : "memory");
;         __builtin_amdgcn_s_barrier();
;         asm volatile("" ::: "memory");
;         { const int nslot = (st + NS - 1) % NS; SG_STAGE(st + NS - 1, nslot); }
.LBB0_1388:
	s_mul_i32 s15, s7, 0xab
	s_bfe_u32 s15, s15, 0x70009
	s_mul_i32 s15, s15, 3
	s_sub_i32 s15, s7, s15
	s_and_b32 s15, s15, 0xff
	s_and_b32 s16, s10, 0x3c0
	s_mul_i32 s15, s15, 0xa000
	s_lshl_b32 s34, s16, 1
	s_add_i32 s15, s6, s15
	s_waitcnt vmcnt(5)
	s_cmp_lt_u32 s9, 0x96000
	s_cbranch_scc1 .Lsgw5
	s_waitcnt vmcnt(0)
.Lsgw5:
	s_barrier
	s_cmp_ge_u32 s9, 0x8c000
	s_cbranch_scc1 .Lsgn5
	v_lshl_add_u64 v[52:53], v[42:43], 0, s[34:35]
	s_mov_b32 m0, s15
	v_lshl_add_u64 v[54:55], v[40:41], 0, s[34:35]
	global_load_lds_dwordx4 v[52:53], off
	s_add_i32 m0, s15, 0x2000
	v_lshl_add_u64 v[56:57], v[54:55], 0, s[58:59]
	global_load_lds_dwordx4 v[54:55], off
	s_add_i32 m0, s15, 0x4000
	v_lshl_add_u64 v[58:59], v[54:55], 0, s[50:51]
	global_load_lds_dwordx4 v[56:57], off
	s_add_i32 m0, s15, 0x6000
	v_lshl_add_u64 v[60:61], v[54:55], 0, s[60:61]
	global_load_lds_dwordx4 v[58:59], off
	s_add_i32 m0, s15, 0x8000
	global_load_lds_dwordx4 v[60:61], off
; #define LAS __attribute__((address_space(3)))
;     DI void row8(int row, int col, f32x4 v0, f32x4 v1, float r, int) const {
;         v0 = v0 * r; v1 = v1 * r;
;         if (MODE == 1) {
; #pragma unroll
;             for (int j = 0; j < 4; ++j) { const float a = v0[j] > 0.f ? v0[j] : 0.f, b = v1[j] > 0.f ? v1[j] : 0.f; v0[j] = a * a; v1[j] = b * b; } }
;         *(u32x4*)(O + (size_t)row * ldc + col) = pack8(v0, v1);
; template <int RA, int NP, int NS, int KT, class R8>
; DI void small_gemm(LAS unsigned char* lds, const bf16* __restrict__ A, const bf16* __restrict__ Bt, int K, int row_base, int col_base, const R8& e, int tid, int wave, int lane) {
;     ...
;         { const int nslot = (st + NS - 1) % NS; SG_STAGE(st + NS - 1, nslot); }
;         const LAS unsigned char* sb0 = lds + (st % NS) * STAGE;
; #pragma unroll
;         for (int t = 0; t < KT; ++t) {
;             const LAS unsigned char* sb = sb0 + t * SUB;
;             bf16x8 af[RA][2], bfr[NP][2][2];
; #pragma unroll
;             for (int ra = 0; ra < RA; ++ra) { af[ra][0] = *(const LAS bf16x8*)(sb + aoff[ra]); af[ra][1] = *(const LAS bf16x8*)(sb + aoff[ra] + 1024); }
; #pragma unroll
;             for (int np = 0; np < NP; ++np)
; #pragma unroll
;                 for (int n = 0; n < 2; ++n) { bfr[np][n][0] = *(const LAS bf16x8*)(sb + boff[np][n]); bfr[np][n][1] = *(const LAS bf16x8*)(sb + boff[np][n] + 1024); }
; #pragma unroll
;             for (int ks = 0; ks < 2; ++ks)
; #pragma unroll
;                 for (int ra = 0; ra < RA; ++ra)
; #pragma unroll
;                     for (int np = 0; np < NP; ++np) { acc[ra][np][0] = __builtin_amdgcn_mfma_f32_16x16x32_bf16(bfr[np][0][ks], af[ra][ks], acc[ra][np][0], 0, 0, 0); acc[ra][np][1] = __builtin_amdgcn_mfma_f32_16x16x32_bf16(bfr[np][1][ks], af[ra][ks], acc[ra][np][1], 0, 0, 0); }
;         }
;     }
;     ...
;     asm volatile("s_waitcnt vmcnt(0)" ::: "memory");
;     __builtin_amdgcn_s_barrier();
;     asm volatile("" ::: "memory");
; #pragma unroll
;     for (int ra = 0; ra < RA; ++ra) {
;         const int row = r0 + 16 * ra + fr;
; #pragma unroll
;         for (int np = 0; np < NP; ++np) {
;             if constexpr (R8::HAS_PRE) e.row8p(row, c0 + 32 * np + 8 * fq, acc[ra][np][0], acc[ra][np][1], prew[ra][np], fq);
;             else e.row8(row, c0 + 32 * np + 8 * fq, acc[ra][np][0], acc[ra][np][1], rsv[ra], fq);
;         }
;     }
.Lsgn5:
	s_mul_hi_u32 s14, s11, 0xaaaaaaab
	s_lshr_b32 s14, s14, 1
	s_mul_i32 s14, s14, 0x1e000
	s_add_i32 s18, s8, s9
	v_subrev_u32_e32 v62, s14, v48
	s_add_i32 s17, s9, 0
	v_subrev_u32_e32 v63, s14, v51
	v_subrev_u32_e32 v64, s14, v49
	v_add_u32_e32 v74, s18, v62
	v_add_u32_e32 v72, s17, v64
	v_add_u32_e32 v73, s17, v63
	ds_read_b128 v[52:55], v74 offset:8192
	ds_read_b128 v[56:59], v72
	ds_read_b128 v[60:63], v74 offset:10240
	ds_read_b128 v[64:67], v74 offset:12288
	ds_read_b128 v[68:71], v74 offset:14336
	s_waitcnt lgkmcnt(0)
	v_mfma_f32_16x16x32_bf16 v[28:31], v[52:55], v[56:59], v[28:31]
	s_add_i32 s11, s11, 1
	s_add_i32 s9, s9, 0xa000
	s_add_i32 s10, s10, 64
	v_mfma_f32_16x16x32_bf16 v[32:35], v[60:63], v[56:59], v[32:35]
	s_add_i32 s7, s7, 1
	s_cmp_lg_u32 s9, 0xa0000
	v_mfma_f32_16x16x32_bf16 v[20:23], v[64:67], v[56:59], v[20:23]
	v_mfma_f32_16x16x32_bf16 v[24:27], v[68:71], v[56:59], v[24:27]
	ds_read_b128 v[56:59], v73
	s_waitcnt lgkmcnt(0)
	v_mfma_f32_16x16x32_bf16 v[12:15], v[52:55], v[56:59], v[12:15]
	v_subrev_u32_e32 v52, s14, v50
	v_add_u32_e32 v73, s17, v52
	ds_read_b128 v[52:55], v74 offset:9216
	v_mfma_f32_16x16x32_bf16 v[16:19], v[60:63], v[56:59], v[16:19]
	ds_read_b128 v[60:63], v74 offset:11264
	v_mfma_f32_16x16x32_bf16 v[4:7], v[64:67], v[56:59], v[4:7]
	ds_read_b128 v[64:67], v74 offset:13312
	v_mfma_f32_16x16x32_bf16 v[8:11], v[68:71], v[56:59], v[8:11]
	ds_read_b128 v[68:71], v74 offset:15360
	ds_read_b128 v[56:59], v72 offset:1024
	s_waitcnt lgkmcnt(0)
	v_mfma_f32_16x16x32_bf16 v[28:31], v[52:55], v[56:59], v[28:31]
	v_mfma_f32_16x16x32_bf16 v[32:35], v[60:63], v[56:59], v[32:35]
	v_mfma_f32_16x16x32_bf16 v[20:23], v[64:67], v[56:59], v[20:23]
	v_mfma_f32_16x16x32_bf16 v[24:27], v[68:71], v[56:59], v[24:27]
	ds_read_b128 v[56:59], v73
	s_waitcnt lgkmcnt(0)
	v_mfma_f32_16x16x32_bf16 v[12:15], v[52:55], v[56:59], v[12:15]
	v_mfma_f32_16x16x32_bf16 v[16:19], v[60:63], v[56:59], v[16:19]
	v_mfma_f32_16x16x32_bf16 v[4:7], v[64:67], v[56:59], v[4:7]
	v_mfma_f32_16x16x32_bf16 v[8:11], v[68:71], v[56:59], v[8:11]
	s_cbranch_scc1 .LBB0_1388
	v_add_f32_e32 v41, v44, v45
	v_add_f32_e32 v40, v46, v47
	v_mov_b32_e32 v42, v41
	v_mov_b32_e32 v43, v40
	s_nop 0
	v_permlane32_swap_b32_e32 v41, v42
	v_permlane32_swap_b32_e32 v40, v43
	v_add_f32_e32 v40, v40, v43
	v_add_f32_e32 v41, v41, v42
	v_fmamk_f32 v40, v40, 0x3a800000, v1
	v_fmamk_f32 v41, v41, 0x3a800000, v1
	v_rsq_f32_e32 v40, v40
	v_rsq_f32_e32 v42, v41
	s_lshl_b32 s6, s13, 2
	s_sub_i32 s6, s12, s6
	s_lshl_b32 s6, s6, 6
	v_pk_mul_f32 v[30:31], v[42:43], v[30:31] op_sel_hi:[0,1]
	v_pk_mul_f32 v[28:29], v[42:43], v[28:29] op_sel_hi:[0,1]
	v_pk_mul_f32 v[32:33], v[42:43], v[32:33] op_sel_hi:[0,1]
	v_pk_mul_f32 v[14:15], v[40:41], v[14:15] op_sel_hi:[0,1]
	v_pk_mul_f32 v[12:13], v[40:41], v[12:13] op_sel_hi:[0,1]
	v_pk_mul_f32 v[16:17], v[40:41], v[16:17] op_sel_hi:[0,1]
	s_add_i32 s6, s6, s3
	v_pk_mul_f32 v[34:35], v[42:43], v[34:35] op_sel_hi:[0,1]
	v_max_f32_e32 v29, 0, v29
	v_max_f32_e32 v28, 0, v28
	v_max_f32_e32 v33, 0, v33
	v_max_f32_e32 v32, 0, v32
	v_max_f32_e32 v31, 0, v31
	v_max_f32_e32 v30, 0, v30
	v_max_f32_e32 v13, 0, v13
	v_max_f32_e32 v12, 0, v12
	v_max_f32_e32 v17, 0, v17
	v_max_f32_e32 v16, 0, v16
	v_max_f32_e32 v15, 0, v15
	v_max_f32_e32 v14, 0, v14
	v_or_b32_e32 v44, s6, v3
	v_pk_mul_f32 v[28:29], v[28:29], v[28:29]
	v_pk_mul_f32 v[32:33], v[32:33], v[32:33]
	v_pk_mul_f32 v[30:31], v[30:31], v[30:31]
	v_max_f32_e32 v35, 0, v35
	v_max_f32_e32 v34, 0, v34
	v_pk_mul_f32 v[22:23], v[42:43], v[22:23] op_sel_hi:[0,1]
	v_pk_mul_f32 v[20:21], v[42:43], v[20:21] op_sel_hi:[0,1]
	v_pk_mul_f32 v[26:27], v[42:43], v[26:27] op_sel_hi:[0,1]
	v_pk_mul_f32 v[24:25], v[42:43], v[24:25] op_sel_hi:[0,1]
	v_pk_mul_f32 v[18:19], v[40:41], v[18:19] op_sel_hi:[0,1]
	v_pk_mul_f32 v[12:13], v[12:13], v[12:13]
	v_pk_mul_f32 v[16:17], v[16:17], v[16:17]
	v_pk_mul_f32 v[14:15], v[14:15], v[14:15]
	v_pk_mul_f32 v[6:7], v[40:41], v[6:7] op_sel_hi:[0,1]
	v_pk_mul_f32 v[4:5], v[40:41], v[4:5] op_sel_hi:[0,1]
	v_pk_mul_f32 v[10:11], v[40:41], v[10:11] op_sel_hi:[0,1]
	v_pk_mul_f32 v[8:9], v[40:41], v[8:9] op_sel_hi:[0,1]
	v_pk_mul_f32 v[34:35], v[34:35], v[34:35]
	v_cvt_pk_bf16_f32 v28, v28, v29
	v_cvt_pk_bf16_f32 v29, v30, v31
	v_cvt_pk_bf16_f32 v30, v32, v33
	v_lshlrev_b64 v[32:33], 13, v[38:39]
	v_ashrrev_i32_e32 v45, 31, v44
	v_max_f32_e32 v21, 0, v21
	v_max_f32_e32 v20, 0, v20
	v_max_f32_e32 v25, 0, v25
	v_max_f32_e32 v24, 0, v24
	v_max_f32_e32 v23, 0, v23
	v_max_f32_e32 v22, 0, v22
	v_max_f32_e32 v27, 0, v27
	v_max_f32_e32 v26, 0, v26
	v_max_f32_e32 v19, 0, v19
	v_max_f32_e32 v18, 0, v18
	v_cvt_pk_bf16_f32 v12, v12, v13
	v_cvt_pk_bf16_f32 v13, v14, v15
	v_cvt_pk_bf16_f32 v14, v16, v17
	v_lshlrev_b64 v[16:17], 13, v[36:37]
	v_max_f32_e32 v5, 0, v5
	v_max_f32_e32 v4, 0, v4
	v_max_f32_e32 v9, 0, v9
	v_max_f32_e32 v8, 0, v8
	v_max_f32_e32 v7, 0, v7
	v_max_f32_e32 v6, 0, v6
	v_max_f32_e32 v11, 0, v11
	v_max_f32_e32 v10, 0, v10
	v_cvt_pk_bf16_f32 v31, v34, v35
	v_lshl_add_u64 v[32:33], s[4:5], 0, v[32:33]
	v_lshlrev_b64 v[34:35], 1, v[44:45]
	v_pk_mul_f32 v[20:21], v[20:21], v[20:21]
	v_pk_mul_f32 v[24:25], v[24:25], v[24:25]
	v_pk_mul_f32 v[22:23], v[22:23], v[22:23]
	v_pk_mul_f32 v[26:27], v[26:27], v[26:27]
	v_pk_mul_f32 v[18:19], v[18:19], v[18:19]
	v_lshl_add_u64 v[16:17], s[4:5], 0, v[16:17]
	v_pk_mul_f32 v[4:5], v[4:5], v[4:5]
	v_pk_mul_f32 v[8:9], v[8:9], v[8:9]
	v_pk_mul_f32 v[6:7], v[6:7], v[6:7]
	v_pk_mul_f32 v[10:11], v[10:11], v[10:11]
	v_lshl_add_u64 v[32:33], v[32:33], 0, v[34:35]
	v_cvt_pk_bf16_f32 v20, v20, v21
	v_cvt_pk_bf16_f32 v21, v22, v23
	v_cvt_pk_bf16_f32 v22, v24, v25
	v_cvt_pk_bf16_f32 v23, v26, v27
	v_cvt_pk_bf16_f32 v15, v18, v19
	v_lshl_add_u64 v[16:17], v[16:17], 0, v[34:35]
	v_cvt_pk_bf16_f32 v4, v4, v5
	v_cvt_pk_bf16_f32 v5, v6, v7
	v_cvt_pk_bf16_f32 v6, v8, v9
	v_cvt_pk_bf16_f32 v7, v10, v11
	s_mov_b64 s[4:5], s[48:49]
	s_mov_b32 s8, s2
	s_waitcnt vmcnt(0)
	s_barrier
	global_store_dwordx4 v[32:33], v[28:31], off
	global_store_dwordx4 v[32:33], v[20:23], off offset:64
	global_store_dwordx4 v[16:17], v[12:15], off
	global_store_dwordx4 v[16:17], v[4:7], off offset:64
	s_getreg_b32 s3, hwreg(HW_REG_XCC_ID, 0, 4)
	s_waitcnt vmcnt(0)
	s_waitcnt vmcnt(0)
	v_readfirstlane_b32 s6, v0
	s_nop 3
	s_lshr_b32 s6, s6, 6
	s_cmp_eq_u32 s6, 1
	s_cbranch_scc0 .Lgb_noinv10
	buffer_inv sc1

;     DI void row8p(int row, int col, f32x4 v0, f32x4 v1, const u32x4 w, int fq) const {
;         f32x4 x0 = (f32x4){bf_lo(w.x), bf_hi(w.x), bf_lo(w.y), bf_hi(w.y)}, x1 = (f32x4){bf_lo(w.z), bf_hi(w.z), bf_lo(w.w), bf_hi(w.w)};
; template <int RA, int NP, int NS, int KT, class R8>
; DI void small_gemm(LAS unsigned char* lds, const bf16* __restrict__ A, const bf16* __restrict__ Bt, int K, int row_base, int col_base, const R8& e, int tid, int wave, int lane) {
;     ...
;     for (int st = 0; st < NT; ++st) {
;         asm volatile("s_waitcnt vmcnt(%0)" :: "n"((NS - 2) * L) : "memory");
;         __builtin_amdgcn_s_barrier();
;         asm volatile("" ::: "memory");
;         { const int nslot = (st + NS - 1) % NS; SG_STAGE(st + NS - 1, nslot); }
;         const LAS unsigned char* sb0 = lds + (st % NS) * STAGE;
; #pragma unroll
;         for (int t = 0; t < KT; ++t) {
;             const LAS unsigned char* sb = sb0 + t * SUB;
;             bf16x8 af[RA][2], bfr[NP][2][2];
; #pragma unroll
;             for (int ra = 0; ra < RA; ++ra) { af[ra][0] = *(const LAS bf16x8*)(sb + aoff[ra]); af[ra][1] = *(const LAS bf16x8*)(sb + aoff[ra] + 1024); }
; #pragma unroll
;             for (int np = 0; np < NP; ++np)
; #pragma unroll
;                 for (int n = 0; n < 2; ++n) { bfr[np][n][0] = *(const LAS bf16x8*)(sb + boff[np][n]); bfr[np][n][1] = *(const LAS bf16x8*)(sb + boff[np][n] + 1024); }
; #pragma unroll
;             for (int ks = 0; ks < 2; ++ks)
; #pragma unroll
;                 for (int ra = 0; ra < RA; ++ra)
; #pragma unroll
;                     for (int np = 0; np < NP; ++np) { acc[ra][np][0] = __builtin_amdgcn_mfma_f32_16x16x32_bf16(bfr[np][0][ks], af[ra][ks], acc[ra][np][0], 0, 0, 0); acc[ra][np][1] = __builtin_amdgcn_mfma_f32_16x16x32_bf16(bfr[np][1][ks], af[ra][ks], acc[ra][np][1], 0, 0, 0); }
;         }
;     }
;     ...
;     asm volatile("s_waitcnt vmcnt(0)" ::: "memory");
;     __builtin_amdgcn_s_barrier();
;     asm volatile("" ::: "memory");
; #pragma unroll
;     for (int ra = 0; ra < RA; ++ra) {
;         const int row = r0 + 16 * ra + fr;
; #pragma unroll
;         for (int np = 0; np < NP; ++np) {
;             if constexpr (R8::HAS_PRE) e.row8p(row, c0 + 32 * np + 8 * fq, acc[ra][np][0], acc[ra][np][1], prew[ra][np], fq);
;             else e.row8(row, c0 + 32 * np + 8 * fq, acc[ra][np][0], acc[ra][np][1], rsv[ra], fq);
;         }
;     }
.LBB0_1500:
	s_add_i32 s8, s7, 0x18000
	s_and_b32 s9, s6, 0xf80
	s_and_b32 s8, s8, 0x18000
	s_lshl_b32 s34, s9, 1
	s_add_i32 s8, s4, s8
	s_waitcnt vmcnt(8)
	s_cmpk_lt_u32 s6, 0x1080
	s_cbranch_scc1 .Lsgw3
	s_waitcnt vmcnt(4)
	s_cmpk_lt_u32 s6, 0x1100
	s_cbranch_scc1 .Lsgw3
	s_waitcnt vmcnt(0)
.Lsgw3:
	s_barrier
	s_cmpk_ge_u32 s6, 0x1000
	s_cbranch_scc1 .Lsgn3
	v_lshl_add_u64 v[26:27], v[22:23], 0, s[34:35]
	s_mov_b32 m0, s8
	v_lshl_add_u64 v[28:29], v[20:21], 0, s[34:35]
	global_load_lds_dwordx4 v[26:27], off
	s_add_i32 m0, s8, 0x2000
	v_lshl_add_u64 v[30:31], v[26:27], 0, s[52:53]
	global_load_lds_dwordx4 v[28:29], off
	s_add_i32 m0, s8, 0x4000
	v_lshl_add_u64 v[32:33], v[28:29], 0, s[52:53]
	global_load_lds_dwordx4 v[30:31], off
	s_add_i32 m0, s8, 0x6000
	global_load_lds_dwordx4 v[32:33], off
.Lsgn3:
	s_and_b32 s8, s7, 0x18000
	s_add_i32 s8, s8, 0
	s_add_i32 s9, s5, s8
	v_add_u32_e32 v42, s8, v25
	v_add_u32_e32 v43, s9, v3
	ds_read_b128 v[26:29], v42 offset:8192
	ds_read_b128 v[30:33], v43
	ds_read_b128 v[34:37], v42 offset:10240
	s_waitcnt lgkmcnt(0)
	v_mfma_f32_16x16x32_bf16 v[8:11], v[26:29], v[30:33], v[8:11]
	ds_read_b128 v[26:29], v42 offset:9216
	ds_read_b128 v[38:41], v43 offset:1024
	s_addk_i32 s6, 0x80
	s_add_i32 s7, s7, 0x8000
	v_mfma_f32_16x16x32_bf16 v[12:15], v[34:37], v[30:33], v[12:15]
	ds_read_b128 v[30:33], v42 offset:11264
	s_cmpk_eq_i32 s6, 0x1180
	s_waitcnt lgkmcnt(0)
	v_mfma_f32_16x16x32_bf16 v[8:11], v[26:29], v[38:41], v[8:11]
	ds_read_b128 v[26:29], v42 offset:24576
	ds_read_b128 v[34:37], v43 offset:16384
	v_mfma_f32_16x16x32_bf16 v[12:15], v[30:33], v[38:41], v[12:15]
	ds_read_b128 v[30:33], v42 offset:26624
	s_waitcnt lgkmcnt(0)
	v_mfma_f32_16x16x32_bf16 v[8:11], v[26:29], v[34:37], v[8:11]
	ds_read_b128 v[26:29], v42 offset:25600
	v_mfma_f32_16x16x32_bf16 v[12:15], v[30:33], v[34:37], v[12:15]
	ds_read_b128 v[30:33], v43 offset:17408
	s_waitcnt lgkmcnt(0)
	v_mfma_f32_16x16x32_bf16 v[8:11], v[26:29], v[30:33], v[8:11]
	ds_read_b128 v[26:29], v42 offset:27648
	s_waitcnt lgkmcnt(0)
	v_mfma_f32_16x16x32_bf16 v[12:15], v[26:29], v[30:33], v[12:15]
	s_cbranch_scc0 .LBB0_1500
	s_waitcnt vmcnt(0)
	v_lshlrev_b32_e32 v20, 16, v4
	v_and_b32_e32 v21, 0xffff0000, v4
	v_lshlrev_b32_e32 v4, 16, v5
	v_and_b32_e32 v5, 0xffff0000, v5
	v_lshlrev_b32_e32 v22, 16, v6
	v_and_b32_e32 v23, 0xffff0000, v6
	v_lshlrev_b32_e32 v6, 16, v7
	v_and_b32_e32 v7, 0xffff0000, v7
	v_pk_add_f32 v[10:11], v[10:11], v[4:5]
	v_pk_add_f32 v[8:9], v[8:9], v[20:21]
	v_pk_add_f32 v[14:15], v[14:15], v[6:7]
	v_pk_add_f32 v[12:13], v[12:13], v[22:23]
	v_cvt_pk_bf16_f32 v4, v8, v9
	v_cvt_pk_bf16_f32 v5, v10, v11
	v_cvt_pk_bf16_f32 v6, v12, v13
	v_cvt_pk_bf16_f32 v7, v14, v15
	s_waitcnt vmcnt(0)
	s_barrier
	global_store_dwordx4 v[18:19], v[4:7], off
	v_mul_f32_e32 v3, v9, v9
	v_fmac_f32_e32 v3, v8, v8
	v_mul_f32_e32 v4, v11, v11
	v_fmac_f32_e32 v4, v10, v10
	v_add_f32_e32 v3, v3, v4
	v_mul_f32_e32 v4, v13, v13
	v_mul_f32_e32 v5, v15, v15
	v_fmac_f32_e32 v4, v12, v12
	v_fmac_f32_e32 v5, v14, v14
	v_add_f32_e32 v4, v4, v5
	v_add_f32_e32 v3, v3, v4
	v_mov_b32_e32 v4, v3
	s_nop 1
	v_permlane16_swap_b32_e32 v3, v4
	v_add_f32_e32 v3, v3, v4
	v_mov_b32_e32 v4, v3
	v_cmp_gt_u32_e32 vcc, 16, v24
	s_nop 0
	v_permlane32_swap_b32_e32 v3, v4
	s_and_saveexec_b64 s[4:5], vcc
	s_cbranch_execz .LBB0_1503
	v_lshlrev_b64 v[6:7], 7, v[16:17]
	s_ashr_i32 s6, s3, 5
	s_ashr_i32 s7, s6, 31
	v_add_f32_e32 v3, v3, v4
	v_lshl_add_u64 v[4:5], s[0:1], 0, v[6:7]
	v_lshl_add_u64 v[4:5], s[6:7], 2, v[4:5]
	global_store_dword v[4:5], v3, off
